# grid barrier: top counter level removed, each XCD last arriver bumps all generation words, all workgroups poll their own generation word
# speedup vs baseline: 1.0482x; 1.0059x over previous
.LBB0_524:
	s_or_b64 exec, exec, s[2:3]
	v_cvt_f32_u32_e32 v5, v3
	s_waitcnt vmcnt(0)
	v_readfirstlane_b32 s2, v4
	v_sub_u32_e32 v4, 0, v3
	v_rcp_iflag_f32_e32 v5, v5
	v_add_u32_e32 v6, s2, v0
	v_mul_f32_e32 v5, 0x4f7ffffe, v5
	v_cvt_u32_f32_e32 v5, v5
	v_mul_lo_u32 v0, v4, v5
	v_mul_hi_u32 v0, v5, v0
	v_add_u32_e32 v0, v5, v0
	v_mul_hi_u32 v0, v6, v0
	v_mul_lo_u32 v4, v0, v3
	v_sub_u32_e32 v4, v6, v4
	v_add_u32_e32 v5, 1, v0
	v_cmp_ge_u32_e32 vcc, v4, v3
	s_nop 1
	v_cndmask_b32_e32 v0, v0, v5, vcc
	v_sub_u32_e32 v5, v4, v3
	v_cndmask_b32_e32 v4, v4, v5, vcc
	v_add_u32_e32 v5, 1, v0
	v_cmp_ge_u32_e32 vcc, v4, v3
	v_add_u32_e32 v4, 1, v6
	s_nop 0
	v_cndmask_b32_e32 v0, v0, v5, vcc
	v_mul_lo_u32 v5, v3, v0
	v_add_u32_e32 v3, v5, v3
	v_cmp_ne_u32_e32 vcc, v4, v3
	s_cbranch_vccnz .Lxb_poll
	buffer_wbl2 sc1
	s_waitcnt vmcnt(0)
	s_add_u32 s28, s62, 0xfa92400
	s_addc_u32 s29, s63, 0
	global_atomic_add v1, v243, s[28:29]
	global_atomic_add v1, v243, s[28:29] offset:256
	global_atomic_add v1, v243, s[28:29] offset:512
	global_atomic_add v1, v243, s[28:29] offset:768
	global_atomic_add v1, v243, s[28:29] offset:1024
	global_atomic_add v1, v243, s[28:29] offset:1280
	global_atomic_add v1, v243, s[28:29] offset:1536
	global_atomic_add v1, v243, s[28:29] offset:1792
	global_atomic_add v1, v243, s[28:29] offset:2048
	global_atomic_add v1, v243, s[28:29] offset:2304
	global_atomic_add v1, v243, s[28:29] offset:2560
	global_atomic_add v1, v243, s[28:29] offset:2816
	global_atomic_add v1, v243, s[28:29] offset:3072
	global_atomic_add v1, v243, s[28:29] offset:3328
	global_atomic_add v1, v243, s[28:29] offset:3584
	global_atomic_add v1, v243, s[28:29] offset:3840
.Lxb_poll:
	v_readlane_b32 s20, v253, 17
	v_readlane_b32 s21, v253, 18
	s_waitcnt lgkmcnt(0)
	s_nop 3
	v_add_u32_e32 v7, 1, v0
	v_mul_lo_u32 v7, v7, v2
	global_load_dword v2, v1, s[20:21] sc1
	buffer_inv sc1
	s_waitcnt vmcnt(0)
	v_sub_u32_e32 v2, v2, v7
	v_cmp_gt_i32_e32 vcc, 0, v2
	s_and_saveexec_b64 s[20:21], vcc
	s_cbranch_execz .LBB0_537
	s_mov_b32 s35, 1
	s_mov_b64 s[22:23], 0
	s_branch .LBB0_528

.LBB0_530:
	v_readlane_b32 s30, v253, 17
	v_readlane_b32 s31, v253, 18
	s_add_i32 s35, s35, 1
	s_mov_b64 s[36:37], -1
	s_nop 2
	global_load_dword v2, v1, s[30:31] sc1
	s_waitcnt vmcnt(0)
	v_sub_u32_e32 v2, v2, v7
	v_cmp_le_i32_e32 vcc, 0, v2
	s_orn2_b64 s[30:31], vcc, exec
	s_branch .LBB0_527

.LBB0_537:
	s_or_b64 exec, exec, s[20:21]
	s_waitcnt vmcnt(0)
	s_waitcnt vmcnt(0)
.LBB0_558:
	s_or_b64 exec, exec, s[0:1]
	s_mov_b64 s[0:1], 0
	s_waitcnt lgkmcnt(0)
	s_barrier
